# layer-1 weight prep partly moved into idle tails of layer-0 GEMM phases (workgroups without split-K/context tiles convert w_in/w_f/w_mla blocks early)
# speedup vs baseline: 1.0067x; 1.0067x over previous
.LBB0_586:
	v_readlane_b32 s90, v245, 61
	v_readlane_b32 s92, v245, 59
	v_readlane_b32 s96, v245, 56
	v_readlane_b32 s16, v245, 53
	v_readlane_b32 s88, v245, 63
	v_readlane_b32 s91, v245, 62
	v_readlane_b32 s93, v245, 60
	v_readlane_b32 s94, v245, 58
	v_readlane_b32 s97, v245, 57
	v_readlane_b32 s95, v245, 55
	v_readlane_b32 s17, v245, 54
	s_barrier
	s_cmp_lt_u32 s88, 64
	s_cbranch_scc1 .Lwph6_skip
	s_load_dword s59, s[90:91], 0xd8
	v_mbcnt_lo_u32_b32 v100, -1, 0
	v_mbcnt_hi_u32_b32 v100, -1, v100
	s_lshr_b32 s69, s94, 6
	s_lshl_b32 s82, s69, 10
	s_lshl_b32 s83, s69, 1
	s_lshr_b32 s98, s69, 2
	v_lshrrev_b32_e32 v101, 5, v100
	v_and_b32_e32 v113, 31, v100
	s_add_i32 s70, s83, 0
	v_add_u32_e32 v102, s70, v101
	s_add_i32 s70, s98, 0
	v_xor_b32_e32 v106, s70, v113
	v_lshlrev_b32_e32 v106, 4, v106
	s_add_i32 s70, s83, 16
	v_add_u32_e32 v103, s70, v101
	s_add_i32 s70, s98, 2
	v_xor_b32_e32 v107, s70, v113
	v_lshlrev_b32_e32 v107, 4, v107
	s_add_i32 s70, s83, 32
	v_add_u32_e32 v104, s70, v101
	s_add_i32 s70, s98, 4
	v_xor_b32_e32 v108, s70, v113
	v_lshlrev_b32_e32 v108, 4, v108
	s_add_i32 s70, s83, 48
	v_add_u32_e32 v105, s70, v101
	s_add_i32 s70, s98, 6
	v_xor_b32_e32 v109, s70, v113
	v_lshlrev_b32_e32 v109, 4, v109
	s_lshr_b32 s70, s94, 3
	v_lshrrev_b32_e32 v112, 3, v100
	v_add_u32_e32 v112, s70, v112
	v_and_b32_e32 v101, 7, v100
	v_lshlrev_b32_e32 v111, 4, v101
	v_lshrrev_b32_e32 v113, 2, v112
	v_xor_b32_e32 v113, v113, v101
	v_lshlrev_b32_e32 v113, 4, v113
	v_lshl_add_u32 v110, v101, 12, v113
	v_and_b32_e32 v113, 3, v112
	v_lshl_add_u32 v110, v113, 2, v110
	s_waitcnt lgkmcnt(0)
	s_sub_u32 s61, s88, 64
	s_add_u32 s61, s61, 0
	s_mov_b32 s59, 192
	s_mov_b32 s101, 768
	s_mov_b32 s60, s61
	s_mov_b32 s58, -2

.Lwph6_skip:
.LBB0_587:
	s_cmp_lt_i32 s92, 8
	s_cselect_b64 s[8:9], -1, 0
	s_cmp_gt_i32 s92, 7
	s_cselect_b64 s[0:1], -1, 0
	s_cmp_lt_i32 s93, 8
	s_cselect_b64 s[2:3], -1, 0
	s_or_b64 s[0:1], s[0:1], s[2:3]
	s_and_b64 vcc, exec, s[0:1]
	s_cbranch_vccnz .LBB0_647
	s_andn2_b64 vcc, exec, s[16:17]
	s_cbranch_vccnz .LBB0_599
	s_waitcnt vmcnt(0)
	v_readlane_b32 s0, v245, 32
	v_readlane_b32 s1, v245, 33
	s_add_i32 s95, s95, 1
	s_andn2_b64 vcc, exec, s[0:1]
	s_waitcnt vmcnt(0) lgkmcnt(0)
	s_barrier
	s_cbranch_vccnz .LBB0_598
	v_mbcnt_lo_u32_b32 v0, -1, 0
	v_mbcnt_hi_u32_b32 v0, -1, v0
	v_cmp_eq_u32_e32 vcc, 0, v0
	s_and_saveexec_b64 s[2:3], vcc
	s_cbranch_execz .LBB0_597
	v_readlane_b32 s0, v245, 50
	s_lshl_b32 s0, s0, 8
	s_add_u32 s0, s96, s0
	s_addc_u32 s1, s97, 0
	v_mov_b32_e32 v0, 0x1000
	v_mov_b32_e32 v1, 1
	global_atomic_add v0, v0, v1, s[0:1] sc0
	v_readlane_b32 s0, v245, 51
	s_add_u32 s4, s86, 0x4b500
	s_mul_i32 s0, s95, s0
	s_addc_u32 s5, s87, 0
	s_waitcnt vmcnt(0)
	v_add_u32_e32 v0, 1, v0
	v_cmp_eq_u32_e32 vcc, s0, v0
	s_and_saveexec_b64 s[6:7], vcc
	s_cbranch_execz .LBB0_594
	s_mov_b64 s[10:11], exec
	v_mbcnt_lo_u32_b32 v0, s10, 0
	buffer_wbl2 sc1
	s_waitcnt vmcnt(0)
	v_mbcnt_hi_u32_b32 v0, s11, v0
	v_cmp_eq_u32_e32 vcc, 0, v0
	s_and_b64 s[0:1], exec, vcc
	s_mov_b64 exec, s[0:1]
	s_cbranch_execz .LBB0_594
	s_bcnt1_i32_b64 s0, s[10:11]
	v_mov_b32_e32 v0, 0
	v_mov_b32_e32 v1, s0
	global_atomic_add v0, v1, s[4:5]

.LBB0_710:
	s_barrier
	s_cmp_lt_u32 s88, 216
	s_cbranch_scc1 .Lwph9_skip
	s_load_dword s59, s[90:91], 0xd8
	v_mbcnt_lo_u32_b32 v100, -1, 0
	v_mbcnt_hi_u32_b32 v100, -1, v100
	s_lshr_b32 s69, s94, 6
	s_lshl_b32 s82, s69, 10
	s_lshl_b32 s83, s69, 1
	s_lshr_b32 s98, s69, 2
	v_lshrrev_b32_e32 v101, 5, v100
	v_and_b32_e32 v113, 31, v100
	s_add_i32 s70, s83, 0
	v_add_u32_e32 v102, s70, v101
	s_add_i32 s70, s98, 0
	v_xor_b32_e32 v106, s70, v113
	v_lshlrev_b32_e32 v106, 4, v106
	s_add_i32 s70, s83, 16
	v_add_u32_e32 v103, s70, v101
	s_add_i32 s70, s98, 2
	v_xor_b32_e32 v107, s70, v113
	v_lshlrev_b32_e32 v107, 4, v107
	s_add_i32 s70, s83, 32
	v_add_u32_e32 v104, s70, v101
	s_add_i32 s70, s98, 4
	v_xor_b32_e32 v108, s70, v113
	v_lshlrev_b32_e32 v108, 4, v108
	s_add_i32 s70, s83, 48
	v_add_u32_e32 v105, s70, v101
	s_add_i32 s70, s98, 6
	v_xor_b32_e32 v109, s70, v113
	v_lshlrev_b32_e32 v109, 4, v109
	s_lshr_b32 s70, s94, 3
	v_lshrrev_b32_e32 v112, 3, v100
	v_add_u32_e32 v112, s70, v112
	v_and_b32_e32 v101, 7, v100
	v_lshlrev_b32_e32 v111, 4, v101
	v_lshrrev_b32_e32 v113, 2, v112
	v_xor_b32_e32 v113, v113, v101
	v_lshlrev_b32_e32 v113, 4, v113
	v_lshl_add_u32 v110, v101, 12, v113
	v_and_b32_e32 v113, 3, v112
	v_lshl_add_u32 v110, v113, 2, v110
	s_waitcnt lgkmcnt(0)
	s_sub_u32 s61, s88, 216
	s_add_u32 s61, s61, 768
	s_mov_b32 s59, 40
	s_mov_b32 s101, 1968
	s_mov_b32 s60, s61
	s_mov_b32 s58, -2

.Lwph9_skip:
.LBB0_711:
	s_cmp_lt_i32 s92, 11
	s_cselect_b64 s[8:9], -1, 0
	s_cmp_gt_i32 s92, 10
	s_cselect_b64 s[0:1], -1, 0
	s_cmp_lt_i32 s93, 11
	s_cselect_b64 s[4:5], -1, 0
	s_or_b64 s[0:1], s[0:1], s[4:5]
	s_and_b64 vcc, exec, s[0:1]
	s_cbranch_vccnz .LBB0_772
	s_andn2_b64 vcc, exec, s[2:3]
	s_cbranch_vccnz .LBB0_723
	s_waitcnt vmcnt(0)
	v_readlane_b32 s0, v245, 32
	v_readlane_b32 s1, v245, 33
	s_add_i32 s95, s95, 1
	s_andn2_b64 vcc, exec, s[0:1]
	s_waitcnt vmcnt(0) lgkmcnt(0)
	s_barrier
	s_cbranch_vccnz .LBB0_722
	v_mbcnt_lo_u32_b32 v0, -1, 0
	v_mbcnt_hi_u32_b32 v0, -1, v0
	v_cmp_eq_u32_e32 vcc, 0, v0
	s_and_saveexec_b64 s[2:3], vcc
	s_cbranch_execz .LBB0_721
	v_readlane_b32 s0, v245, 50
	s_lshl_b32 s0, s0, 8
	s_add_u32 s0, s96, s0
	s_addc_u32 s1, s97, 0
	v_mov_b32_e32 v0, 0x1000
	v_mov_b32_e32 v1, 1
	global_atomic_add v0, v0, v1, s[0:1] sc0
	v_readlane_b32 s0, v245, 51
	s_add_u32 s4, s86, 0x4b500
	s_mul_i32 s0, s95, s0
	s_addc_u32 s5, s87, 0
	s_waitcnt vmcnt(0)
	v_add_u32_e32 v0, 1, v0
	v_cmp_eq_u32_e32 vcc, s0, v0
	s_and_saveexec_b64 s[6:7], vcc
	s_cbranch_execz .LBB0_718
	s_mov_b64 s[10:11], exec
	v_mbcnt_lo_u32_b32 v0, s10, 0
	buffer_wbl2 sc1
	s_waitcnt vmcnt(0)
	v_mbcnt_hi_u32_b32 v0, s11, v0
	v_cmp_eq_u32_e32 vcc, 0, v0
	s_and_b64 s[0:1], exec, vcc
	s_mov_b64 exec, s[0:1]
	s_cbranch_execz .LBB0_718
	s_bcnt1_i32_b64 s0, s[10:11]
	v_mov_b32_e32 v0, 0
	v_mov_b32_e32 v1, s0
	global_atomic_add v0, v1, s[4:5]

.LBB0_771:
	s_barrier
	s_cmp_lt_u32 s88, 176
	s_cbranch_scc1 .Lwph10_skip
	s_load_dword s59, s[90:91], 0xd8
	v_mbcnt_lo_u32_b32 v100, -1, 0
	v_mbcnt_hi_u32_b32 v100, -1, v100
	s_lshr_b32 s69, s94, 6
	s_lshl_b32 s82, s69, 10
	s_lshl_b32 s83, s69, 1
	s_lshr_b32 s98, s69, 2
	v_lshrrev_b32_e32 v101, 5, v100
	v_and_b32_e32 v113, 31, v100
	s_add_i32 s70, s83, 0
	v_add_u32_e32 v102, s70, v101
	s_add_i32 s70, s98, 0
	v_xor_b32_e32 v106, s70, v113
	v_lshlrev_b32_e32 v106, 4, v106
	s_add_i32 s70, s83, 16
	v_add_u32_e32 v103, s70, v101
	s_add_i32 s70, s98, 2
	v_xor_b32_e32 v107, s70, v113
	v_lshlrev_b32_e32 v107, 4, v107
	s_add_i32 s70, s83, 32
	v_add_u32_e32 v104, s70, v101
	s_add_i32 s70, s98, 4
	v_xor_b32_e32 v108, s70, v113
	v_lshlrev_b32_e32 v108, 4, v108
	s_add_i32 s70, s83, 48
	v_add_u32_e32 v105, s70, v101
	s_add_i32 s70, s98, 6
	v_xor_b32_e32 v109, s70, v113
	v_lshlrev_b32_e32 v109, 4, v109
	s_lshr_b32 s70, s94, 3
	v_lshrrev_b32_e32 v112, 3, v100
	v_add_u32_e32 v112, s70, v112
	v_and_b32_e32 v101, 7, v100
	v_lshlrev_b32_e32 v111, 4, v101
	v_lshrrev_b32_e32 v113, 2, v112
	v_xor_b32_e32 v113, v113, v101
	v_lshlrev_b32_e32 v113, 4, v113
	v_lshl_add_u32 v110, v101, 12, v113
	v_and_b32_e32 v113, 3, v112
	v_lshl_add_u32 v110, v113, 2, v110
	s_waitcnt lgkmcnt(0)
	s_sub_u32 s61, s88, 176
	s_add_u32 s61, s61, 1968
	s_mov_b32 s59, 80
	s_mov_b32 s101, 2608
	s_mov_b32 s60, s61
	s_mov_b32 s58, -2

.Lwph10_skip:
.LBB0_772:
	s_cmp_lt_i32 s92, 12
	s_cselect_b64 s[6:7], -1, 0
	s_cmp_gt_i32 s92, 11
	s_cselect_b64 s[0:1], -1, 0
	s_cmp_lt_i32 s93, 12
	s_cselect_b64 s[2:3], -1, 0
	s_or_b64 s[0:1], s[0:1], s[2:3]
	s_and_b64 vcc, exec, s[0:1]
	s_cbranch_vccnz .LBB0_925
	s_andn2_b64 vcc, exec, s[8:9]
	s_cbranch_vccnz .LBB0_784
	s_waitcnt vmcnt(0)
	v_readlane_b32 s0, v245, 32
	v_readlane_b32 s1, v245, 33
	s_add_i32 s95, s95, 1
	s_andn2_b64 vcc, exec, s[0:1]
	s_waitcnt vmcnt(0) lgkmcnt(0)
	s_barrier
	s_cbranch_vccnz .LBB0_783
	v_mbcnt_lo_u32_b32 v0, -1, 0
	v_mbcnt_hi_u32_b32 v0, -1, v0
	v_cmp_eq_u32_e32 vcc, 0, v0
	s_and_saveexec_b64 s[2:3], vcc
	s_cbranch_execz .LBB0_782
	v_readlane_b32 s0, v245, 50
	s_lshl_b32 s0, s0, 8
	s_add_u32 s0, s96, s0
	s_addc_u32 s1, s97, 0
	v_mov_b32_e32 v0, 0x1000
	v_mov_b32_e32 v1, 1
	global_atomic_add v0, v0, v1, s[0:1] sc0
	v_readlane_b32 s0, v245, 51
	s_add_u32 s4, s86, 0x4b500
	s_mul_i32 s0, s95, s0
	s_addc_u32 s5, s87, 0
	s_waitcnt vmcnt(0)
	v_add_u32_e32 v0, 1, v0
	v_cmp_eq_u32_e32 vcc, s0, v0
	s_and_saveexec_b64 s[8:9], vcc
	s_cbranch_execz .LBB0_779
	s_mov_b64 s[10:11], exec
	v_mbcnt_lo_u32_b32 v0, s10, 0
	buffer_wbl2 sc1
	s_waitcnt vmcnt(0)
	v_mbcnt_hi_u32_b32 v0, s11, v0
	v_cmp_eq_u32_e32 vcc, 0, v0
	s_and_b64 s[0:1], exec, vcc
	s_mov_b64 exec, s[0:1]
	s_cbranch_execz .LBB0_779
	s_bcnt1_i32_b64 s0, s[10:11]
	v_mov_b32_e32 v0, 0
	v_mov_b32_e32 v1, s0
	global_atomic_add v0, v1, s[4:5]

.LBB0_784:
	s_mov_b64 s[4:5], 0
	s_load_dword s12, s[90:91], 0xd8
	v_mbcnt_lo_u32_b32 v0, -1, 0
	v_mbcnt_hi_u32_b32 v77, -1, v0
	v_or_b32_e32 v76, s94, v77
	s_mov_b32 s0, s88
	s_add_u32 s8, s86, s4
	s_waitcnt lgkmcnt(0)
	s_mov_b32 s1, s12
	v_mov_b32_e32 v78, v76
	s_mov_b32 s13, s12
	s_addc_u32 s9, s87, s5
	s_abs_i32 s22, s13
	v_cvt_f32_u32_e32 v2, s22
	v_lshlrev_b32_e32 v0, 2, v78
	v_and_b32_e32 v84, 60, v0
	s_sub_i32 s2, 0, s22
	v_rcp_iflag_f32_e32 v0, v2
	s_mov_b32 s14, s88
	s_add_i32 s15, s14, s13
	v_mul_f32_e32 v0, 0x4f7ffffe, v0
	v_cvt_u32_f32_e32 v0, v0
	s_abs_i32 s1, s15
	s_ashr_i32 s0, s15, 31
	v_ashrrev_i32_e32 v80, 3, v78
	v_readfirstlane_b32 s23, v0
	s_mul_i32 s2, s2, s23
	s_mul_hi_u32 s2, s23, s2
	s_add_i32 s23, s23, s2
	s_mul_hi_u32 s2, s1, s23
	s_mul_i32 s2, s2, s22
	s_sub_i32 s1, s1, s2
	s_sub_i32 s2, s1, s22
	s_cmp_ge_u32 s1, s22
	s_cselect_b32 s1, s2, s1
	s_sub_i32 s2, s1, s22
	s_cmp_ge_u32 s1, s22
	s_cselect_b32 s1, s2, s1
	s_xor_b32 s1, s1, s0
	v_lshlrev_b32_e32 v2, 3, v78
	s_sub_i32 s24, s1, s0
	v_ashrrev_i32_e32 v79, 4, v78
	v_mov_b32_e32 v1, 0
	v_lshl_add_u32 v81, v84, 2, 0
	v_and_b32_e32 v82, 56, v2
	s_cmpk_lt_i32 s24, 0x480
	v_lshl_add_u32 v83, v80, 2, 0
	s_load_dword s59, s[90:91], 0xd8
	v_mbcnt_lo_u32_b32 v100, -1, 0
	v_mbcnt_hi_u32_b32 v100, -1, v100
	s_lshr_b32 s69, s94, 6
	s_lshl_b32 s82, s69, 10
	s_lshl_b32 s83, s69, 1
	s_lshr_b32 s98, s69, 2
	v_lshrrev_b32_e32 v101, 5, v100
	v_and_b32_e32 v113, 31, v100
	s_add_i32 s70, s83, 0
	v_add_u32_e32 v102, s70, v101
	s_add_i32 s70, s98, 0
	v_xor_b32_e32 v106, s70, v113
	v_lshlrev_b32_e32 v106, 4, v106
	s_add_i32 s70, s83, 16
	v_add_u32_e32 v103, s70, v101
	s_add_i32 s70, s98, 2
	v_xor_b32_e32 v107, s70, v113
	v_lshlrev_b32_e32 v107, 4, v107
	s_add_i32 s70, s83, 32
	v_add_u32_e32 v104, s70, v101
	s_add_i32 s70, s98, 4
	v_xor_b32_e32 v108, s70, v113
	v_lshlrev_b32_e32 v108, 4, v108
	s_add_i32 s70, s83, 48
	v_add_u32_e32 v105, s70, v101
	s_add_i32 s70, s98, 6
	v_xor_b32_e32 v109, s70, v113
	v_lshlrev_b32_e32 v109, 4, v109
	s_lshr_b32 s70, s94, 3
	v_lshrrev_b32_e32 v112, 3, v100
	v_add_u32_e32 v112, s70, v112
	v_and_b32_e32 v101, 7, v100
	v_lshlrev_b32_e32 v111, 4, v101
	v_lshrrev_b32_e32 v113, 2, v112
	v_xor_b32_e32 v113, v113, v101
	v_lshlrev_b32_e32 v113, 4, v113
	v_lshl_add_u32 v110, v101, 12, v113
	v_and_b32_e32 v113, 3, v112
	v_lshl_add_u32 v110, v113, 2, v110
	s_waitcnt lgkmcnt(0)
	s_add_u32 s61, s88, 2608
	s_mov_b32 s60, s61
	s_mov_b32 s101, 7520
	s_mov_b32 s58, -2
